# work-ticket prefetch for dynamic WG mixer tasks (atomic issued at task start, 2 barriers per task removed) + ret task prologue param/Q loads issued together
# speedup vs baseline: 1.0124x; 1.0005x over previous
; __device__ __forceinline__ void mixer_phase(ParamsCP pp, int layer, LAS unsigned char* lds, int tid) {
;     ...
;     for (;;) {
;         __syncthreads();
;         if (tid == 0) *flag = atomicAdd(ctrw, 1u);
;         __syncthreads();
;         const int q = (int)__builtin_amdgcn_readfirstlane((int)*flag);
;         if (q >= TW_TOTAL) break;
.LBB0_381:
	v_mov_b32_e32 v0, s70
	s_branch .Lmx_read

; __device__ __forceinline__ void wg_ret_task(ParamsCP pp, int layer, LAS unsigned char* lds, int b, int h, int qb, int tid_in) {
;     ...
;     const int jrA = qb * 16 + wave, jrB = jrA + 8; const bool actA = jrA < 129, actB = jrB < 129; const int jA = actA ? jrA : 128, jB = actB ? jrB : 128;
;     const int qrowA = tile_row(b, jA), qrowB = tile_row(b, jB);
; __device__ __forceinline__ void mixer_phase(ParamsCP pp, int layer, LAS unsigned char* lds, int tid) {
;     ...
;         const int q = (int)__builtin_amdgcn_readfirstlane((int)*flag);
;         if (q >= TW_TOTAL) break;
;         if (q < TW_DIFF) { const int b = q / 68, rem = q - b * 68, h = rem / 17, qb = rem - h * 17; wg_diff_task(pp, layer, lds, b, h, qb, tid); }
;         else { const int q2 = q - TW_DIFF; const int b = q2 / 72, rem = q2 - b * 72, h = rem / 9, qb = rem - h * 9; wg_ret_task(pp, layer, lds, b, h, qb, tid); }
.Lmx_read:
	ds_read_b32 v0, v0
	s_mov_b64 s[4:5], -1
	s_waitcnt lgkmcnt(0)
	v_readfirstlane_b32 s30, v0
	s_cmpk_gt_i32 s30, 0x8bf
	s_cbranch_scc1 .LBB0_382
	s_cmpk_gt_i32 s30, 0x43f
	s_cbranch_scc0 .LBB0_436
	s_add_i32 s4, s30, 0xfffffbc0
	s_mul_i32 s5, s4, 0xe38f
	s_lshr_b32 s8, s5, 22
	s_mul_i32 s5, s8, 0xffffffb8
	s_add_i32 s4, s5, s4
	s_mul_i32 s5, s4, 0x1c72
	s_lshr_b32 s9, s5, 31
	s_lshr_b32 s5, s5, 16
	s_add_i32 s5, s5, s9
	s_sext_i32_i16 s48, s5
	s_mul_i32 s5, s48, -9
	v_mov_b32_e32 v24, v206
	s_add_i32 s5, s5, s4
	s_nop 0
	v_readfirstlane_b32 s4, v24
	s_ashr_i32 s37, s4, 6
	s_lshl_b32 s4, s5, 4
	s_add_i32 s37, s37, s4
	s_cmpk_lt_i32 s37, 0x81
	s_cselect_b64 s[24:25], -1, 0
	s_and_b64 s[4:5], s[24:25], exec
	s_cselect_b32 s61, s37, 0x80
	s_cmp_lg_u32 s61, 0
	s_cbranch_scc0 .LBB0_448
	s_lshl_b32 s4, s8, 11
	s_lshl_b32 s5, s61, 4
	s_add_i32 s4, s5, s4
	s_add_i32 s41, s4, 0xf0
	s_cbranch_execnz .LBB0_392

; __device__ __forceinline__ void wg_ret_task(ParamsCP pp, int layer, LAS unsigned char* lds, int b, int h, int qb, int tid_in) {
;     ...
;     const bf16_t* PROJ = (const bf16_t*)(pp->ws + WS_BIG + BIG_PROJ); const bf16_t* VT = (const bf16_t*)(pp->ws + WS_BIG + BIG_VT);
;     const int lane = tid & 63, wave = __builtin_amdgcn_readfirstlane(tid >> 6), c16 = lane & 15, quad = lane >> 4;
;     const size_t qcol = C_RQ + h * 64, kcol = C_RK + h * 64;
;     const int vrow0 = V_RET + h * 128;
;     const int jrA = qb * 16 + wave, jrB = jrA + 8; const bool actA = jrA < 129, actB = jrB < 129; const int jA = actA ? jrA : 128, jB = actB ? jrB : 128;
;     const int qrowA = tile_row(b, jA), qrowB = tile_row(b, jB);
;     const bool kcopy = tid < 256; const int krow = (tid & 255) >> 3, kch = tid & 7, vr = tid >> 2, vc = tid & 3;
;     const float lgf = log1pf(-exp2f(-pp->in[4][layer * 8 + h])) * LOG2E, lgb = log1pf(-exp2f(-pp->in[5][layer * 8 + h])) * LOG2E;
;     const int tqA = 16 * jA + c16, tqB = 16 * jB + c16;
;     bf16x8 qA[2], qB[2];
;     { const bf16_t* qp = PROJ + (size_t)(qrowA + c16) * PP + qcol + 8 * quad; qA[0] = *(const bf16x8*)qp; qA[1] = *(const bf16x8*)(qp + 32);
;       const bf16_t* qp2 = PROJ + (size_t)(qrowB + c16) * PP + qcol + 8 * quad; qB[0] = *(const bf16x8*)qp2; qB[1] = *(const bf16x8*)(qp2 + 32); }
; __device__ __forceinline__ void mixer_phase(ParamsCP pp, int layer, LAS unsigned char* lds, int tid) {
;     ...
;         if (tid == 0) *flag = atomicAdd(ctrw, 1u);
.LBB0_395:
	s_and_saveexec_b64 s[4:5], s[6:7]
	s_cbranch_execz .Lmx_r_noat
	v_mov_b32_e32 v252, 1
	global_atomic_add v252, v1, v252, s[80:81] sc0
.Lmx_r_noat:
	s_mov_b64 exec, s[4:5]
	s_load_dwordx4 s[8:11], s[0:1], 0x20
	s_add_i32 s12, s35, s48
	s_lshl_b32 s4, s48, 6
	s_ashr_i32 s13, s12, 31
	s_ashr_i32 s5, s4, 31
	s_lshl_b64 s[12:13], s[12:13], 2
	s_lshl_b64 s[38:39], s[4:5], 1
	s_waitcnt lgkmcnt(0)
	s_add_u32 s8, s8, s12
	s_addc_u32 s9, s9, s13
	global_load_dword v0, v1, s[8:9]
	s_add_u32 s10, s10, s12
	s_addc_u32 s11, s11, s13
	global_load_dword v21, v1, s[10:11]
	s_mov_b32 s15, 0x42fc0000
	v_and_b32_e32 v122, 15, v24
	v_add_u32_e32 v2, s41, v122
	v_add_u32_e32 v4, s40, v122
	v_ashrrev_i32_e32 v3, 31, v2
	v_ashrrev_i32_e32 v5, 31, v4
	v_lshlrev_b64 v[2:3], 12, v[2:3]
	v_lshlrev_b64 v[4:5], 12, v[4:5]
	v_bfe_u32 v32, v24, 4, 2
	v_lshl_add_u64 v[2:3], s[84:85], 0, v[2:3]
	v_lshl_add_u64 v[4:5], s[84:85], 0, v[4:5]
	v_mov_b32_e32 v29, v1
	v_lshlrev_b32_e32 v28, 4, v32
	v_and_b32_e32 v30, 7, v24
	v_bfe_u32 v123, v24, 3, 5
	v_lshlrev_b32_e32 v116, 4, v30
	v_lshl_add_u64 v[2:3], v[2:3], 0, s[38:39]
	v_lshl_add_u64 v[4:5], v[4:5], 0, s[38:39]
	v_lshl_add_u64 v[2:3], v[2:3], 0, v[28:29]
	v_lshl_add_u64 v[16:17], v[4:5], 0, v[28:29]
	global_load_dwordx4 v[4:7], v[2:3], off
	global_load_dwordx4 v[8:11], v[2:3], off offset:64
	global_load_dwordx4 v[12:15], v[16:17], off
	s_nop 0
	global_load_dwordx4 v[16:19], v[16:17], off offset:64
	s_waitcnt vmcnt(5)
	v_cmp_lt_f32_e32 vcc, s15, v0
	s_and_b64 s[8:9], vcc, exec
	s_cselect_b32 s14, 0xffffffc0, 0
	v_cndmask_b32_e32 v20, 0, v240, vcc
	v_sub_f32_e32 v0, v20, v0
	v_exp_f32_e32 v0, v0
	s_waitcnt vmcnt(4)
	v_cmp_lt_f32_e32 vcc, s15, v21
	s_and_b64 s[8:9], vcc, exec
	s_cselect_b32 s10, 0xffffffc0, 0
	v_cndmask_b32_e32 v22, 0, v240, vcc
	v_ldexp_f32 v33, v0, s14
	v_sub_f32_e32 v0, v22, v21
	v_exp_f32_e32 v0, v0
	v_sub_f32_e32 v35, 1.0, v33
	v_frexp_mant_f32_e32 v2, v35
	s_mov_b32 s8, 0x3f2aaaab
	v_ldexp_f32 v29, v0, s10
	v_sub_f32_e32 v34, 1.0, v29
	v_frexp_mant_f32_e32 v0, v34
	v_cmp_gt_f32_e64 s[12:13], s8, v2
	v_cmp_gt_f32_e32 vcc, s8, v0
	s_movk_i32 s8, 0xff
	v_mov_b32_e32 v2, v1
	v_mov_b32_e32 v3, v1
	v_cmp_lt_i32_e64 s[14:15], s8, v24
	s_movk_i32 s8, 0x100
	v_mov_b32_e32 v0, v1
	v_mov_b64_e32 v[22:23], v[2:3]
	v_cmp_gt_i32_e64 s[8:9], s8, v24
	v_mov_b64_e32 v[20:21], v[0:1]
	s_barrier
	s_and_saveexec_b64 s[38:39], s[8:9]
	s_cbranch_execz .LBB0_397
	v_mov_b32_e32 v0, s49
	v_mov_b32_e32 v2, s76
	v_cmp_gt_u32_e64 s[10:11], 16, v123
	v_mov_b32_e32 v117, v1
	s_nop 0
	v_cndmask_b32_e64 v0, v0, v2, s[10:11]
	v_add_lshl_u32 v0, v0, v123, 12
	v_lshl_add_u64 v[2:3], s[84:85], 0, v[0:1]
	v_lshl_add_u64 v[2:3], s[4:5], 1, v[2:3]
	v_lshl_add_u64 v[2:3], v[2:3], 0, v[116:117]
	global_load_dwordx4 v[20:23], v[2:3], off offset:1024

; #define RT_COMMIT(KR, VR, buf) do { LAS unsigned char* bb_ = lds + (buf) * MX_BUF; \
;         if (kcopy) *(LAS u32x4*)(bb_ + krow * KP + kch * 16) = KR; *(LAS u32x4*)(bb_ + MX_KBYTES + vr * VP + vc * 16) = VR; } while (0)
; __device__ __forceinline__ void wg_ret_task(ParamsCP pp, int layer, LAS unsigned char* lds, int b, int h, int qb, int tid_in) {
;     ...
;     RT_ISSUE(kr0s, vr0s, 0); RT_COMMIT(kr0s, vr0s, 0); RT_ISSUE(kr1s, vr1s, 1);
; __device__ __forceinline__ void mixer_phase(ParamsCP pp, int layer, LAS unsigned char* lds, int tid) {
;     ...
;         if (tid == 0) *flag = atomicAdd(ctrw, 1u);
.LBB0_399:
	s_or_b64 exec, exec, s[38:39]
	s_movk_i32 s38, 0x50
	v_mul_lo_u32 v0, v3, s38
	v_add_u32_e32 v0, 0, v0
	v_lshlrev_b32_e32 v2, 4, v2
	v_add_u32_e32 v125, v0, v2
	v_lshlrev_b32_e32 v30, 3, v30
	s_waitcnt vmcnt(0)
	ds_write_b128 v125, v[24:27] offset:8704
	s_and_saveexec_b64 s[38:39], s[6:7]
	s_cbranch_execz .Lmx_r_nowr
	v_mov_b32_e32 v253, s70
	ds_write_b32 v253, v252
.Lmx_r_nowr:
	s_mov_b64 exec, s[38:39]
	s_and_saveexec_b64 s[38:39], s[14:15]
	s_xor_b64 s[14:15], exec, s[38:39]
	v_mov_b32_e32 v31, v1
	s_or_saveexec_b64 s[14:15], s[14:15]
	v_mov_b32_e32 v2, v1
	v_mov_b32_e32 v3, v1
	v_mov_b32_e32 v0, v1
	v_mov_b64_e32 v[26:27], v[2:3]
	s_or_b32 s38, s64, 0x110
	v_mov_b64_e32 v[24:25], v[0:1]
	s_xor_b64 exec, exec, s[14:15]
	s_cbranch_execz .LBB0_403
	v_add_lshl_u32 v24, s38, v123, 12
	v_mov_b32_e32 v25, v1
	v_lshl_add_u64 v[24:25], s[84:85], 0, v[24:25]
	v_lshl_add_u64 v[24:25], s[4:5], 1, v[24:25]
	v_mov_b32_e32 v117, v1
	v_lshl_add_u64 v[24:25], v[24:25], 0, v[116:117]
	global_load_dwordx4 v[24:27], v[24:25], off offset:1024
	v_mov_b32_e32 v31, v1

; __device__ __forceinline__ float uniform_f(float x) { return __uint_as_float((unsigned)__builtin_amdgcn_readfirstlane((int)__float_as_uint(x))); }
; #define DF_COMMIT(buf) do { LAS unsigned char* bb_ = lds + (buf) * DF_BUF; \
;         _Pragma("unroll") for (int i_ = 0; i_ < 2; ++i_) { const int id_ = tid + 512 * i_, kr_ = id_ >> 5, kc_ = id_ & 31, vr_ = id_ >> 2, vc_ = id_ & 3; \
;             *(LAS u32x4*)(bb_ + kr_ * DF_KP + kc_ * 16) = kreg[i_]; *(LAS u32x4*)(bb_ + DF_KBYTES + vr_ * VP + vc_ * 16) = vreg[i_]; } } while (0)
; __device__ __forceinline__ void wg_diff_task(ParamsCP pp, int layer, LAS unsigned char* lds, int b, int h, int qb, int tid_in) {
;     ...
;     const bf16_t* PROJ = (const bf16_t*)(pp->ws + WS_BIG + BIG_PROJ); const bf16_t* VT = (const bf16_t*)(pp->ws + WS_BIG + BIG_VT);
;     const int lane = tid & 63, wave = __builtin_amdgcn_readfirstlane(tid >> 6), c16 = lane & 15, quad = lane >> 4;
;     const size_t qcol = PBUF + h * 256, kcol = PBUF + 1024 + h * 256;
;     const int vrow0 = V_DIFF + h * 256;
;     const int jraw = qb * 8 + wave; const bool active = jraw < 129; const int jq = active ? jraw : 128;
;     const int qrow0 = tile_row(b, jq);
;     const float* misc = (const float*)(pp->ws + WS_MISC) + 16 * layer;
;     const float lam = uniform_f(misc[0]), cb = uniform_f(misc[1] * LOG2E), sc = 0.08838834764831845f * LOG2E;
;     bf16x8 qf0[4], qf1[4];
;     { const bf16_t* qp = PROJ + (size_t)(qrow0 + c16) * PP + qcol + 8 * quad;
; #pragma unroll
;         for (int ks = 0; ks < 4; ++ks) { qf0[ks] = *(const bf16x8*)(qp + 32 * ks); qf1[ks] = *(const bf16x8*)(qp + 128 + 32 * ks); } }
;     f32x4 acc0[16], acc1[16];
; #pragma unroll
;     for (int e0 = 0; e0 < 16; ++e0) { acc0[e0] = (f32x4){0.f, 0.f, 0.f, 0.f}; acc1[e0] = (f32x4){0.f, 0.f, 0.f, 0.f}; }
;     float ls0 = 0.f, ls1 = 0.f;
;     u32x4 kreg[2], vreg[2];
;     ...
;     __syncthreads();
;     DF_ISSUE(0); DF_COMMIT(0);
;     __syncthreads();
.Lmx_d_noat:
	s_mov_b64 exec, s[4:5]
	v_and_b32_e32 v207, 15, v2
	v_add_u32_e32 v4, s30, v207
	s_lshl_b32 s24, s10, 8
	v_ashrrev_i32_e32 v5, 31, v4
	s_ashr_i32 s25, s24, 31
	v_lshlrev_b64 v[4:5], 12, v[4:5]
	v_bfe_u32 v208, v2, 4, 2
	v_lshl_add_u64 v[4:5], s[84:85], 0, v[4:5]
	s_lshl_b64 s[4:5], s[24:25], 1
	v_lshl_add_u64 v[4:5], v[4:5], 0, s[4:5]
	v_lshlrev_b32_e32 v0, 4, v208
	v_lshl_add_u64 v[4:5], v[4:5], 0, v[0:1]
	s_mov_b64 s[10:11], 0x8100000
	s_add_i32 s38, s24, 0x400
	v_lshl_add_u64 v[6:7], v[4:5], 0, s[10:11]
	s_mov_b32 s10, 0x8100000
	s_bitset1_b32 s9, 8
	v_add_co_u32_e32 v4, vcc, s10, v4
	s_add_u32 s4, s84, s4
	v_lshlrev_b32_e32 v10, 4, v2
	v_addc_co_u32_e32 v5, vcc, 0, v5, vcc
	s_addc_u32 s5, s85, s5
	v_and_b32_e32 v180, 0x1f0, v10
	v_mov_b32_e32 v181, v1
	global_load_dwordx4 v[114:117], v[4:5], off
	global_load_dwordx2 v[178:179], v1, s[20:21]
	global_load_dwordx4 v[118:121], v[6:7], off offset:64
	global_load_dwordx4 v[122:125], v[6:7], off offset:256
	global_load_dwordx4 v[126:129], v[6:7], off offset:320
	global_load_dwordx4 v[134:137], v[6:7], off offset:128
	global_load_dwordx4 v[138:141], v[6:7], off offset:192
	global_load_dwordx4 v[142:145], v[6:7], off offset:384
	global_load_dwordx4 v[146:149], v[6:7], off offset:448
	v_and_b32_e32 v3, 2, v2
	v_lshl_add_u64 v[4:5], s[4:5], 0, v[180:181]
	s_mov_b64 s[4:5], 0x8100800
	v_lshlrev_b32_e32 v6, 3, v2
	v_lshl_add_u64 v[182:183], v[4:5], 0, s[4:5]
	v_mov_b32_e32 v4, s9
	v_mov_b32_e32 v11, s8
	v_cmp_eq_u32_e64 s[8:9], 0, v3
	v_and_b32_e32 v181, 8, v6
	v_ashrrev_i32_e32 v209, 5, v2
	v_cndmask_b32_e64 v3, v4, v11, s[8:9]
	v_or_b32_e32 v4, v3, v181
	v_mov_b32_e32 v3, s37
	v_cmp_gt_i32_e64 s[10:11], 16, v209
	v_ashrrev_i32_e32 v12, 2, v2
	v_add_u32_e32 v2, 0x200, v2
	v_cndmask_b32_e64 v6, v3, v11, s[10:11]
	v_add_u32_e32 v6, v6, v209
	v_ashrrev_i32_e32 v7, 31, v6
	v_ashrrev_i32_e32 v5, 31, v4
	v_lshlrev_b64 v[6:7], 12, v[6:7]
	v_ashrrev_i32_e32 v210, 5, v2
	v_lshl_add_u64 v[4:5], v[4:5], 1, s[16:17]
	v_lshl_add_u64 v[6:7], v[182:183], 0, v[6:7]
	v_add_u32_e32 v13, s38, v12
	s_mov_b32 s41, 0x10200
	v_cmp_gt_i32_e64 s[12:13], 16, v210
	s_waitcnt vmcnt(63) expcnt(7) lgkmcnt(15)
	s_barrier
	v_mad_i64_i32 v[8:9], s[4:5], v13, s41, v[4:5]
	global_load_dwordx4 v[162:165], v[6:7], off
	global_load_dwordx4 v[166:169], v[8:9], off
	v_ashrrev_i32_e32 v6, 2, v2
	v_cndmask_b32_e64 v2, v3, v11, s[12:13]
	v_add_u32_e32 v2, v2, v210
	v_ashrrev_i32_e32 v3, 31, v2
	v_lshlrev_b64 v[2:3], 12, v[2:3]
	v_lshl_add_u64 v[2:3], v[182:183], 0, v[2:3]
	v_add_u32_e32 v7, s38, v6
	global_load_dwordx4 v[170:173], v[2:3], off
	v_mad_i64_i32 v[2:3], s[4:5], v7, s41, v[4:5]
	global_load_dwordx4 v[174:177], v[2:3], off
	v_mad_i64_i32 v[184:185], s[4:5], v13, s41, 0
	v_mad_i64_i32 v[186:187], s[4:5], v7, s41, 0
	v_mov_b32_e32 v2, 0x3fb8aa3b
	s_movk_i32 s5, 0x210
	v_and_b32_e32 v212, 48, v10
	v_mul_lo_u32 v213, v209, s5
	s_movk_i32 s4, 0x50
	v_add_u32_e32 v3, 0, v212
	v_mul_lo_u32 v214, v12, s4
	v_mul_lo_u32 v215, v210, s5
	v_mul_lo_u32 v216, v6, s4
	v_mov_b32_e32 v22, 0
	s_mov_b32 s38, 3
	s_mov_b32 s39, 0
	v_lshlrev_b32_e32 v211, 3, v208
	v_mul_u32_u24_e32 v217, 0x210, v207
	v_mul_u32_u24_e32 v218, 0x50, v207
	v_mov_b32_e32 v23, v22
	v_mov_b32_e32 v24, v22
	v_mov_b32_e32 v25, v22
	v_mov_b32_e32 v50, v22
	v_mov_b32_e32 v51, v22
	v_mov_b32_e32 v52, v22
	v_mov_b32_e32 v53, v22
	v_mov_b32_e32 v58, v22
	v_mov_b32_e32 v59, v22
	s_waitcnt vmcnt(11)
	v_readfirstlane_b32 s40, v179
	v_mov_b32_e32 v60, v22
	v_mov_b32_e32 v61, v22
	v_mul_f32_e32 v179, s40, v2
	v_add_u32_e32 v2, 0, v180
	v_add_u32_e32 v4, v2, v213
	v_add_u32_e32 v2, v2, v215
	s_add_i32 s40, s37, 32
	v_mov_b32_e32 v70, v22
	v_mov_b32_e32 v71, v22
	v_mov_b32_e32 v72, v22
	v_mov_b32_e32 v73, v22
	v_mov_b32_e32 v82, v22
	v_mov_b32_e32 v83, v22
	v_mov_b32_e32 v84, v22
	v_mov_b32_e32 v85, v22
	v_mov_b32_e32 v90, v22
	v_mov_b32_e32 v91, v22
	v_mov_b32_e32 v92, v22
	v_mov_b32_e32 v93, v22
	v_mov_b32_e32 v102, v22
	v_mov_b32_e32 v103, v22
	v_mov_b32_e32 v104, v22
	v_mov_b32_e32 v105, v22
	v_mov_b32_e32 v130, v22
	v_mov_b32_e32 v131, v22
	v_mov_b32_e32 v132, v22
	v_mov_b32_e32 v133, v22
	v_mov_b32_e32 v42, v22
	v_mov_b32_e32 v43, v22
	v_mov_b32_e32 v44, v22
	v_mov_b32_e32 v45, v22
	v_mov_b32_e32 v34, v22
	v_mov_b32_e32 v35, v22
	v_mov_b32_e32 v36, v22
	v_mov_b32_e32 v37, v22
	v_mov_b32_e32 v26, v22
	v_mov_b32_e32 v27, v22
	v_mov_b32_e32 v28, v22
	s_waitcnt vmcnt(3)
	ds_write_b128 v4, v[162:165]
	v_add_u32_e32 v4, v3, v214
	s_waitcnt vmcnt(2)
	ds_write_b128 v4, v[166:169] offset:16896
	v_mov_b32_e32 v29, v22
	v_mov_b32_e32 v18, v22
	v_mov_b32_e32 v19, v22
	v_mov_b32_e32 v20, v22
	v_mov_b32_e32 v21, v22
	v_mov_b32_e32 v14, v22
	s_waitcnt vmcnt(1)
	ds_write_b128 v2, v[170:173]
	v_add_u32_e32 v2, v3, v216
	v_mov_b32_e32 v15, v22
	s_waitcnt vmcnt(0)
	ds_write_b128 v2, v[174:177] offset:16896
	v_mov_b32_e32 v16, v22
	v_mov_b32_e32 v17, v22
	v_mov_b32_e32 v10, v22
	v_mov_b32_e32 v11, v22
	v_mov_b32_e32 v12, v22
	v_mov_b32_e32 v13, v22
	v_mov_b32_e32 v6, v22
	v_mov_b32_e32 v7, v22
	v_mov_b32_e32 v8, v22
	v_mov_b32_e32 v9, v22
	v_mov_b32_e32 v2, v22
	v_mov_b32_e32 v3, v22
	v_mov_b32_e32 v4, v22
	v_mov_b32_e32 v5, v22
	v_mov_b32_e32 v158, v22
	v_mov_b32_e32 v159, v22
	v_mov_b32_e32 v160, v22
	v_mov_b32_e32 v161, v22
	v_mov_b32_e32 v154, v22
	v_mov_b32_e32 v155, v22
	v_mov_b32_e32 v156, v22
	v_mov_b32_e32 v157, v22
	v_mov_b32_e32 v150, v22
	v_mov_b32_e32 v151, v22
	v_mov_b32_e32 v152, v22
	v_mov_b32_e32 v153, v22
	v_mov_b32_e32 v110, v22
	v_mov_b32_e32 v111, v22
	v_mov_b32_e32 v112, v22
	v_mov_b32_e32 v113, v22
	v_mov_b32_e32 v106, v22
	v_mov_b32_e32 v107, v22
	v_mov_b32_e32 v108, v22
	v_mov_b32_e32 v109, v22
	v_mov_b32_e32 v98, v22
	v_mov_b32_e32 v99, v22
	v_mov_b32_e32 v100, v22
	v_mov_b32_e32 v101, v22
	v_mov_b32_e32 v94, v22
	v_mov_b32_e32 v95, v22
	v_mov_b32_e32 v96, v22
	v_mov_b32_e32 v97, v22
	v_mov_b32_e32 v86, v22
	v_mov_b32_e32 v87, v22
	v_mov_b32_e32 v88, v22
	v_mov_b32_e32 v89, v22
	v_mov_b32_e32 v78, v22
	v_mov_b32_e32 v79, v22
	v_mov_b32_e32 v80, v22
	v_mov_b32_e32 v81, v22
	v_mov_b32_e32 v74, v22
	v_mov_b32_e32 v75, v22
	v_mov_b32_e32 v76, v22
	v_mov_b32_e32 v77, v22
	v_mov_b32_e32 v66, v22
	v_mov_b32_e32 v67, v22
	v_mov_b32_e32 v68, v22
	v_mov_b32_e32 v69, v22
	v_mov_b32_e32 v62, v22
	v_mov_b32_e32 v63, v22
	v_mov_b32_e32 v64, v22
	v_mov_b32_e32 v65, v22
	v_mov_b32_e32 v54, v22
	v_mov_b32_e32 v55, v22
	v_mov_b32_e32 v56, v22
	v_mov_b32_e32 v57, v22
	v_mov_b32_e32 v46, v22
	v_mov_b32_e32 v47, v22
	v_mov_b32_e32 v48, v22
	v_mov_b32_e32 v49, v22
	v_mov_b32_e32 v38, v22
	v_mov_b32_e32 v39, v22
	v_mov_b32_e32 v40, v22
	v_mov_b32_e32 v41, v22
	v_mov_b32_e32 v30, v22
	v_mov_b32_e32 v31, v22
	v_mov_b32_e32 v32, v22
	v_mov_b32_e32 v33, v22
	v_mov_b32_e32 v188, v22
	v_mov_b32_e32 v189, v22
	v_readfirstlane_b32 s4, v206
	s_nop 3
	s_bitcmp1_b32 s4, 8
	s_cbranch_scc0 .Lprio_d_skip
	s_setprio 1
; #define DF_COMMIT(buf) do { LAS unsigned char* bb_ = lds + (buf) * DF_BUF; \
;         _Pragma("unroll") for (int i_ = 0; i_ < 2; ++i_) { const int id_ = tid + 512 * i_, kr_ = id_ >> 5, kc_ = id_ & 31, vr_ = id_ >> 2, vc_ = id_ & 3; \
;             *(LAS u32x4*)(bb_ + kr_ * DF_KP + kc_ * 16) = kreg[i_]; *(LAS u32x4*)(bb_ + DF_KBYTES + vr_ * VP + vc_ * 16) = vreg[i_]; } } while (0)
; __device__ __forceinline__ void wg_diff_task(ParamsCP pp, int layer, LAS unsigned char* lds, int b, int h, int qb, int tid_in) {
;     ...
;     __syncthreads();
;     DF_ISSUE(0); DF_COMMIT(0);
;     __syncthreads();
; __device__ __forceinline__ void mixer_phase(ParamsCP pp, int layer, LAS unsigned char* lds, int tid) {
;     ...
;         if (tid == 0) *flag = atomicAdd(ctrw, 1u);
.Lprio_d_skip:
	s_and_saveexec_b64 s[4:5], s[6:7]
	s_cbranch_execz .Lmx_d_nowr
	v_mov_b32_e32 v253, s70
	ds_write_b32 v253, v252
.Lmx_d_nowr:
	s_mov_b64 exec, s[4:5]
	s_waitcnt lgkmcnt(0)
	s_barrier
	s_branch .LBB0_442
